# NA phase: static s_setprio 1 for waves 4-7 for the whole phase (reset at phase end)
# baseline (speedup 1.0000x reference)
.LBB0_1079:
	v_writelane_b32 v238, s84, 4
	s_nop 1
	v_writelane_b32 v238, s85, 5
	v_writelane_b32 v238, s81, 6
	v_writelane_b32 v238, s82, 7
	s_nop 1
	v_writelane_b32 v238, s83, 8
	v_writelane_b32 v238, s80, 9
	v_writelane_b32 v238, s78, 10
	s_nop 1
	v_writelane_b32 v238, s79, 11
	s_or_b64 exec, exec, s[0:1]
	s_waitcnt lgkmcnt(0)
	s_barrier
	s_mov_b32 s0, 1
	s_cmp_eq_u32 s0, 0
	s_cbranch_scc1 .LBB0_1588
	v_readfirstlane_b32 s98, v192
	s_nop 3
	s_lshr_b32 s98, s98, 6
	s_cmp_ge_u32 s98, 4
	s_cbranch_scc0 .Lna_prio_done
	s_setprio 1
.Lna_prio_done:
	s_and_b32 s0, s60, 7
	s_cmp_eq_u32 s0, 0
	s_cselect_b64 s[2:3], -1, 0
	v_writelane_b32 v238, s2, 12
	s_cmp_lg_u32 s0, 0
	s_nop 0
	v_writelane_b32 v238, s3, 13
	s_nop 0
	v_readlane_b32 s90, v238, 9
	s_cbranch_scc1 .LBB0_1082
	v_readlane_b32 s2, v238, 9
	s_and_b32 s0, s2, 7
	s_ashr_i32 s1, s60, 3
	s_mul_i32 s0, s1, s0
	s_lshr_b32 s1, s2, 3
	s_add_i32 s90, s0, s1

.LBB0_1588:
	s_setprio 0
	s_waitcnt vmcnt(0)
	v_readlane_b32 s70, v238, 4
	v_readlane_b32 s71, v238, 5
	s_barrier
	s_and_saveexec_b64 s[0:1], s[70:71]
	v_readlane_b32 s68, v238, 7
	v_readlane_b32 s69, v238, 8
	v_readlane_b32 s67, v238, 6
	s_cbranch_execz .LBB0_1640
	s_add_i32 s3, 0, 0x20000
	v_mov_b32_e32 v0, s3
	s_getreg_b32 s2, hwreg(HW_REG_XCC_ID, 0, 4)
	s_waitcnt vmcnt(0) expcnt(0) lgkmcnt(0)
	ds_read_b32 v2, v0
	s_add_i32 s3, 0, 0x20004
	v_mov_b32_e32 v0, s3
	ds_read_b32 v0, v0
	s_and_b32 s33, s2, 15
	s_waitcnt lgkmcnt(1)
	v_cmp_ne_u32_e32 vcc, 0, v2
	s_cbranch_vccnz .LBB0_1604
	s_add_u32 s2, s64, 0x3000200
	s_addc_u32 s3, s65, 0
	s_add_u32 s4, s64, 0x3000400
	s_addc_u32 s5, s65, 0
	s_add_u32 s6, s64, 0x3000500
	s_addc_u32 s7, s65, 0
	s_add_u32 s8, s64, 0x3000600
	s_addc_u32 s9, s65, 0
	s_add_u32 s10, s64, 0x3000700
	s_addc_u32 s11, s65, 0
	s_add_u32 s12, s64, 0x3000800
	s_addc_u32 s13, s65, 0
	s_add_u32 s14, s64, 0x3000900
	s_addc_u32 s15, s65, 0
	s_add_u32 s16, s64, 0x3000a00
	s_addc_u32 s17, s65, 0
	s_add_u32 s18, s64, 0x3000b00
	s_addc_u32 s19, s65, 0
	s_add_u32 s20, s64, 0x3000c00
	s_addc_u32 s21, s65, 0
	s_add_u32 s22, s64, 0x3000d00
	s_addc_u32 s23, s65, 0
	s_add_u32 s24, s64, 0x3000e00
	s_addc_u32 s25, s65, 0
	s_add_u32 s26, s64, 0x3000f00
	s_addc_u32 s27, s65, 0
	s_add_u32 s28, s64, 0x3001000
	s_addc_u32 s29, s65, 0
	s_add_u32 s30, s64, 0x3001100
	s_addc_u32 s31, s65, 0
	s_add_u32 s34, s64, 0x3001200
	s_addc_u32 s35, s65, 0
	s_mul_i32 s44, s61, s67
	s_add_u32 s36, s64, 0x3001300
	s_mul_i32 s44, s44, s60
	s_addc_u32 s37, s65, 0
	s_mov_b32 s45, 1
	v_mov_b32_e32 v16, 0
	s_branch .LBB0_1592
